# panel exchange: first slot poll delayed by s_sleep 16 instead of 4
# speedup vs baseline: 1.0032x; 1.0032x over previous
.LBB0_563:
	s_waitcnt lgkmcnt(0)
	s_barrier
	s_and_b64 vcc, exec, s[2:3]
	s_cbranch_vccnz .LBB0_565
	v_lshlrev_b64 v[96:97], 5, v[96:97]
	v_lshl_add_u64 v[96:97], s[12:13], 0, v[96:97]
	s_mov_b32 s100, 0x400000
	s_sleep 16
